# weight prep: layers l and l+2 of the same tile handled in one pass (two f32 tiles in flight, second LDS scratch, one barrier pair per two tiles)
# speedup vs baseline: 1.0182x; 1.0025x over previous
.LBB0_17:
	s_load_dword s26, s[0:1], 0xb8
	s_add_u32 s0, s96, 0x1000000
	v_writelane_b32 v253, s0, 32
	s_addc_u32 s0, s97, 0
	s_cmpk_lt_i32 s2, 0xad0
	v_writelane_b32 v253, s0, 33
	s_cselect_b64 s[0:1], -1, 0
	v_cndmask_b32_e64 v1, 0, 1, s[0:1]
	s_lshl_b32 s27, s2, 6
	s_lshl_b32 s40, s2, 2
	s_lshl_b32 s28, s2, 5
	s_mov_b32 s9, 0
	v_cmp_ne_u32_e64 s[0:1], 1, v1
	v_mov_b32_e32 v3, 0
	s_movk_i32 s29, 0x104
	s_movk_i32 s30, 0x5800
	s_movk_i32 s31, 0x80
	s_movk_i32 s34, 0x1800
	s_movk_i32 s35, 0x1400
	s_lshl_b32 s36, s33, 6
	s_lshl_b32 s37, s33, 2
	s_lshl_b32 s41, s33, 5
	v_mov_b32_e32 v1, 0xfffff500
	v_mov_b32_e32 v4, 0x80
	v_mov_b32_e32 v5, 0xbfb8aa3b
	v_mov_b32_e32 v6, 0xbf317218
	s_mov_b32 s42, 0
	s_mov_b64 s[98:99], 0x3000000
	v_writelane_b32 v253, s92, 34
	s_branch .LBB0_20

.LBB0_19:
	s_add_i32 s42, s42, 1
	s_cmp_eq_u32 s42, 2
	s_cbranch_scc1 .LBB0_46

.LBB0_23:
	s_cmpk_gt_i32 s60, 0x17f
	s_cbranch_scc0 .LBB0_31
	s_cmpk_gt_u32 s60, 0x27f
	s_cbranch_scc0 .LBB0_32
	s_cmpk_gt_u32 s60, 0x28f
	s_cbranch_scc0 .LBB0_33
	s_cmpk_gt_u32 s60, 0x80f
	s_mov_b64 s[22:23], -1
	s_cbranch_scc0 .LBB0_28
	v_mov_b32_e32 v7, v209
	s_add_i32 s8, s58, 0x3dfc0
	s_and_b32 s24, s59, 0x3c0
	s_and_b32 s8, s8, 0x3ffc0
	v_ashrrev_i32_e32 v18, 4, v7
	s_lshl_b32 s22, s24, 2
	s_add_u32 s22, s43, s22
	v_lshlrev_b32_e32 v2, 4, v7
	v_add_u32_e32 v14, s8, v18
	s_addc_u32 s23, s44, 0
	v_and_b32_e32 v2, 0xf0, v2
	v_ashrrev_i32_e32 v15, 31, v14
	v_lshl_add_u64 v[12:13], s[22:23], 0, v[2:3]
	v_lshlrev_b64 v[8:9], 12, v[14:15]
	v_add_u32_e32 v14, 32, v14
	v_lshl_add_u64 v[8:9], v[12:13], 0, v[8:9]
	v_ashrrev_i32_e32 v15, 31, v14
	s_mov_b64 s[94:95], 0x1600000
	v_lshl_add_u64 v[30:31], v[8:9], 0, s[94:95]
	global_load_dwordx4 v[8:11], v[8:9], off
	v_lshlrev_b64 v[14:15], 12, v[14:15]
	v_lshl_add_u64 v[12:13], v[12:13], 0, v[14:15]
	v_lshl_add_u64 v[32:33], v[12:13], 0, s[94:95]
	global_load_dwordx4 v[12:15], v[12:13], off
	global_load_dwordx4 v[34:37], v[30:31], off
	global_load_dwordx4 v[38:41], v[32:33], off
	v_ashrrev_i32_e32 v19, 3, v7
	v_lshlrev_b32_e32 v7, 3, v7
	v_and_b32_e32 v7, 56, v7
	v_mul_lo_u32 v18, v18, s29
	v_add_u32_e32 v20, s24, v19
	v_lshlrev_b32_e32 v21, 2, v19
	v_mul_u32_u24_e32 v22, 0x104, v7
	v_add3_u32 v18, 0, v2, v18
	v_lshlrev_b32_e32 v23, 2, v20
	v_add3_u32 v21, 0, v22, v21
	v_lshrrev_b32_e32 v19, 1, v19
	v_lshlrev_b32_e32 v2, 1, v7
	v_add_u32_e32 v7, 0x2080, v18
	v_add_u32_e32 v24, 0x2088, v18
	v_and_b32_e32 v22, 16, v23
	v_add_u32_e32 v23, 0x400, v21
	v_and_b32_e32 v19, 12, v19
	v_and_b32_e32 v20, 0xffffffe3, v20
	v_mov_b64_e32 v[16:17], s[14:15]
	v_or3_b32 v19, v20, v19, v22
	s_movk_i32 s22, 0x1600
	s_lshl_b32 s8, s8, 1
	v_mad_i64_i32 v[16:17], s[22:23], v19, s22, v[16:17]
	v_lshl_add_u64 v[16:17], v[16:17], 0, s[8:9]
	v_lshl_add_u64 v[16:17], v[16:17], 0, v[2:3]
	s_mov_b64 s[22:23], 0
	s_waitcnt vmcnt(3)
	ds_write2_b32 v18, v8, v9 offset1:1
	ds_write2_b32 v18, v10, v11 offset0:2 offset1:3
	s_waitcnt vmcnt(2)
	ds_write2_b32 v7, v12, v13 offset1:1
	ds_write2_b32 v24, v14, v15 offset1:1
	s_waitcnt vmcnt(1)
	v_add_u32_e32 v42, 0x4200, v18
	v_add_u32_e32 v43, 0x4200, v7
	v_add_u32_e32 v44, 0x4200, v24
	ds_write2_b32 v42, v34, v35 offset1:1
	ds_write2_b32 v42, v36, v37 offset0:2 offset1:3
	s_waitcnt vmcnt(0)
	ds_write2_b32 v43, v38, v39 offset1:1
	ds_write2_b32 v44, v40, v41 offset1:1
	v_add_u32_e32 v45, 0x4200, v21
	v_add_u32_e32 v60, 0x4200, v23
	s_waitcnt lgkmcnt(0)
	s_barrier
	ds_read2_b32 v[8:9], v21 offset1:65
	ds_read2_b32 v[10:11], v21 offset0:130 offset1:195
	ds_read2_b32 v[12:13], v23 offset0:4 offset1:69
	ds_read2_b32 v[14:15], v23 offset0:134 offset1:199
	s_waitcnt lgkmcnt(3)
	v_cvt_pk_bf16_f32 v8, v8, v9
	s_waitcnt lgkmcnt(2)
	v_cvt_pk_bf16_f32 v9, v10, v11
	s_waitcnt lgkmcnt(1)
	v_cvt_pk_bf16_f32 v10, v12, v13
	s_waitcnt lgkmcnt(0)
	v_cvt_pk_bf16_f32 v11, v14, v15
	global_store_dwordx4 v[16:17], v[8:11], off
	ds_read2_b32 v[46:47], v45 offset1:65
	ds_read2_b32 v[48:49], v45 offset0:130 offset1:195
	ds_read2_b32 v[50:51], v60 offset0:4 offset1:69
	ds_read2_b32 v[52:53], v60 offset0:134 offset1:199
	v_lshl_add_u64 v[58:59], v[16:17], 0, s[98:99]
	s_waitcnt lgkmcnt(0)
	v_cvt_pk_bf16_f32 v54, v46, v47
	v_cvt_pk_bf16_f32 v55, v48, v49
	v_cvt_pk_bf16_f32 v56, v50, v51
	v_cvt_pk_bf16_f32 v57, v52, v53
	global_store_dwordx4 v[58:59], v[54:57], off
	s_barrier
.LBB0_28:
	s_andn2_b64 vcc, exec, s[22:23]
	s_cbranch_vccnz .LBB0_30
	s_add_i32 s8, s60, 0xfd70
	s_and_b32 s22, s8, 0xffff
	s_mul_i32 s22, s22, 0xba2f
	s_lshr_b32 s23, s22, 16
	s_lshr_b32 s22, s22, 22
	s_mulk_i32 s22, 0x58
	s_sub_i32 s8, s8, s22
	s_lshl_b32 s8, s8, 6
	s_and_b32 s8, s8, 0xffc0
	v_mov_b32_e32 v7, v209
	s_and_b32 s24, s23, 0xffc0
	s_lshl_b32 s22, s8, 2
	s_add_u32 s22, s45, s22
	v_lshlrev_b32_e32 v2, 4, v7
	v_ashrrev_i32_e32 v16, 4, v7
	s_addc_u32 s23, s46, 0
	v_and_b32_e32 v2, 0xf0, v2
	v_lshl_add_u64 v[12:13], s[22:23], 0, v[2:3]
	v_add_u32_e32 v14, s24, v16
	v_mad_i64_i32 v[8:9], s[22:23], v14, s30, v[12:13]
	s_mov_b64 s[94:95], 0x2c00000
	v_lshl_add_u64 v[30:31], v[8:9], 0, s[94:95]
	global_load_dwordx4 v[8:11], v[8:9], off
	v_add_u32_e32 v14, 32, v14
	v_mad_i64_i32 v[12:13], s[22:23], v14, s30, v[12:13]
	v_lshl_add_u64 v[32:33], v[12:13], 0, s[94:95]
	global_load_dwordx4 v[12:15], v[12:13], off
	global_load_dwordx4 v[34:37], v[30:31], off
	global_load_dwordx4 v[38:41], v[32:33], off
	v_ashrrev_i32_e32 v17, 3, v7
	v_lshlrev_b32_e32 v7, 3, v7
	v_mul_lo_u32 v16, v16, s29
	v_and_b32_e32 v7, 56, v7
	v_lshlrev_b32_e32 v18, 2, v17
	v_add3_u32 v20, 0, v2, v16
	v_mul_u32_u24_e32 v2, 0x104, v7
	v_add3_u32 v23, 0, v2, v18
	v_add_u32_e32 v2, s8, v17
	s_movk_i32 s8, 0xaff
	v_cmp_lt_i32_e32 vcc, s8, v2
	v_lshrrev_b32_e32 v19, 1, v17
	v_and_b32_e32 v19, 12, v19
	v_cndmask_b32_e32 v16, 0, v1, vcc
	v_lshlrev_b32_e32 v17, 2, v2
	v_and_b32_e32 v18, 0x63, v2
	v_add_lshl_u32 v2, v16, v2, 1
	v_cndmask_b32_e32 v25, 0, v4, vcc
	v_add_u32_e32 v21, 0x2080, v20
	v_add_u32_e32 v22, 0x2088, v20
	v_add_u32_e32 v24, 0x400, v23
	v_and_b32_e32 v17, 16, v17
	v_and_b32_e32 v26, 0xffffff00, v2
	v_or3_b32 v18, v18, v19, v25
	v_or3_b32 v18, v18, v17, v26
	v_ashrrev_i32_e32 v19, 31, v18
	v_lshlrev_b64 v[18:19], 11, v[18:19]
	v_cndmask_b32_e32 v16, v5, v6, vcc
	s_lshl_b32 s8, s24, 1
	v_lshl_add_u64 v[18:19], s[16:17], 0, v[18:19]
	v_lshlrev_b32_e32 v2, 1, v7
	v_lshl_add_u64 v[18:19], v[18:19], 0, s[8:9]
	v_lshl_add_u64 v[18:19], v[18:19], 0, v[2:3]
	s_waitcnt vmcnt(3)
	ds_write2_b32 v20, v8, v9 offset1:1
	ds_write2_b32 v20, v10, v11 offset0:2 offset1:3
	s_waitcnt vmcnt(2)
	ds_write2_b32 v21, v12, v13 offset1:1
	ds_write2_b32 v22, v14, v15 offset1:1
	s_waitcnt vmcnt(1)
	v_add_u32_e32 v42, 0x4200, v20
	v_add_u32_e32 v43, 0x4200, v21
	v_add_u32_e32 v44, 0x4200, v22
	ds_write2_b32 v42, v34, v35 offset1:1
	ds_write2_b32 v42, v36, v37 offset0:2 offset1:3
	s_waitcnt vmcnt(0)
	ds_write2_b32 v43, v38, v39 offset1:1
	ds_write2_b32 v44, v40, v41 offset1:1
	v_add_u32_e32 v45, 0x4200, v23
	v_add_u32_e32 v60, 0x4200, v24
	s_waitcnt lgkmcnt(0)
	s_barrier
	ds_read2_b32 v[8:9], v23 offset1:65
	ds_read2_b32 v[10:11], v23 offset0:130 offset1:195
	ds_read2_b32 v[12:13], v24 offset0:4 offset1:69
	ds_read2_b32 v[14:15], v24 offset0:134 offset1:199
	s_waitcnt lgkmcnt(3)
	v_pk_mul_f32 v[8:9], v[16:17], v[8:9] op_sel_hi:[0,1]
	s_waitcnt lgkmcnt(2)
	v_pk_mul_f32 v[10:11], v[16:17], v[10:11] op_sel_hi:[0,1]
	s_waitcnt lgkmcnt(1)
	v_pk_mul_f32 v[12:13], v[16:17], v[12:13] op_sel_hi:[0,1]
	s_waitcnt lgkmcnt(0)
	v_pk_mul_f32 v[14:15], v[16:17], v[14:15] op_sel_hi:[0,1]
	v_cvt_pk_bf16_f32 v8, v8, v9
	v_cvt_pk_bf16_f32 v9, v10, v11
	v_cvt_pk_bf16_f32 v10, v12, v13
	v_cvt_pk_bf16_f32 v11, v14, v15
	global_store_dwordx4 v[18:19], v[8:11], off
	ds_read2_b32 v[46:47], v45 offset1:65
	ds_read2_b32 v[48:49], v45 offset0:130 offset1:195
	ds_read2_b32 v[50:51], v60 offset0:4 offset1:69
	ds_read2_b32 v[52:53], v60 offset0:134 offset1:199
	v_lshl_add_u64 v[58:59], v[18:19], 0, s[98:99]
	s_waitcnt lgkmcnt(0)
	v_pk_mul_f32 v[46:47], v[16:17], v[46:47] op_sel_hi:[0,1]
	v_pk_mul_f32 v[48:49], v[16:17], v[48:49] op_sel_hi:[0,1]
	v_pk_mul_f32 v[50:51], v[16:17], v[50:51] op_sel_hi:[0,1]
	v_pk_mul_f32 v[52:53], v[16:17], v[52:53] op_sel_hi:[0,1]
	v_cvt_pk_bf16_f32 v54, v46, v47
	v_cvt_pk_bf16_f32 v55, v48, v49
	v_cvt_pk_bf16_f32 v56, v50, v51
	v_cvt_pk_bf16_f32 v57, v52, v53
	global_store_dwordx4 v[58:59], v[54:57], off
	s_barrier

.LBB0_34:
	s_and_b64 vcc, exec, s[18:19]
	s_cbranch_vccz .LBB0_36
	s_add_i32 s8, s60, 0xfffffd80
	s_lshr_b32 s8, s8, 2
	s_lshl_b64 s[22:23], s[8:9], 16
	s_add_u32 s61, s47, s22
	s_addc_u32 s64, s48, s23
	s_lshl_b64 s[22:23], s[8:9], 15
	s_add_u32 s22, s49, s22
	s_addc_u32 s23, s50, s23
	s_and_b32 s8, s60, 3
	s_lshl_b32 s24, s8, 6
	s_and_b32 s65, s57, 64
	s_add_i32 s25, s24, 0xffffff80
	s_cmp_lt_u32 s8, 2
	s_cselect_b32 s24, s24, s25
	v_mov_b32_e32 v7, v209
	s_ashr_i32 s25, s24, 31
	s_lshl_b64 s[62:63], s[24:25], 2
	v_ashrrev_i32_e32 v16, 4, v7
	s_add_u32 s62, s61, s62
	v_lshlrev_b32_e32 v2, 4, v7
	v_add_u32_e32 v14, s65, v16
	s_addc_u32 s63, s64, s63
	v_and_b32_e32 v2, 0xf0, v2
	v_ashrrev_i32_e32 v15, 31, v14
	v_lshl_add_u64 v[12:13], s[62:63], 0, v[2:3]
	v_lshlrev_b64 v[8:9], 9, v[14:15]
	v_add_u32_e32 v14, 32, v14
	v_lshl_add_u64 v[8:9], v[12:13], 0, v[8:9]
	v_ashrrev_i32_e32 v15, 31, v14
	s_mov_b64 s[94:95], 0x40000
	v_lshl_add_u64 v[30:31], v[8:9], 0, s[94:95]
	global_load_dwordx4 v[8:11], v[8:9], off
	v_lshlrev_b64 v[14:15], 9, v[14:15]
	v_lshl_add_u64 v[12:13], v[12:13], 0, v[14:15]
	v_lshl_add_u64 v[32:33], v[12:13], 0, s[94:95]
	global_load_dwordx4 v[12:15], v[12:13], off
	global_load_dwordx4 v[34:37], v[30:31], off
	global_load_dwordx4 v[38:41], v[32:33], off
	v_ashrrev_i32_e32 v17, 3, v7
	v_lshlrev_b32_e32 v7, 3, v7
	v_mul_lo_u32 v16, v16, s29
	v_and_b32_e32 v7, 56, v7
	v_lshlrev_b32_e32 v18, 2, v17
	v_add3_u32 v19, 0, v2, v16
	v_mul_u32_u24_e32 v2, 0x104, v7
	v_add3_u32 v18, 0, v2, v18
	v_add_u32_e32 v20, 0x2080, v19
	v_add_u32_e32 v21, 0x2088, v19
	v_add_u32_e32 v22, 0x400, v18
	v_add_u32_e32 v16, s24, v17
	v_ashrrev_i32_e32 v17, 31, v16
	v_lshlrev_b64 v[16:17], 8, v[16:17]
	v_lshl_add_u64 v[16:17], s[22:23], 0, v[16:17]
	s_lshl_b32 s8, s65, 1
	v_lshl_add_u64 v[16:17], v[16:17], 0, s[8:9]
	v_lshlrev_b32_e32 v2, 1, v7
	v_lshl_add_u64 v[16:17], v[16:17], 0, v[2:3]
	s_mov_b64 s[22:23], -1
	s_waitcnt vmcnt(3)
	ds_write2_b32 v19, v8, v9 offset1:1
	ds_write2_b32 v19, v10, v11 offset0:2 offset1:3
	s_waitcnt vmcnt(2)
	ds_write2_b32 v20, v12, v13 offset1:1
	ds_write2_b32 v21, v14, v15 offset1:1
	s_waitcnt vmcnt(1)
	v_add_u32_e32 v42, 0x4200, v19
	v_add_u32_e32 v43, 0x4200, v20
	v_add_u32_e32 v44, 0x4200, v21
	ds_write2_b32 v42, v34, v35 offset1:1
	ds_write2_b32 v42, v36, v37 offset0:2 offset1:3
	s_waitcnt vmcnt(0)
	ds_write2_b32 v43, v38, v39 offset1:1
	ds_write2_b32 v44, v40, v41 offset1:1
	v_add_u32_e32 v45, 0x4200, v18
	v_add_u32_e32 v60, 0x4200, v22
	s_waitcnt lgkmcnt(0)
	s_barrier
	ds_read2_b32 v[8:9], v18 offset1:65
	ds_read2_b32 v[10:11], v18 offset0:130 offset1:195
	ds_read2_b32 v[12:13], v22 offset0:4 offset1:69
	ds_read2_b32 v[14:15], v22 offset0:134 offset1:199
	s_waitcnt lgkmcnt(3)
	v_cvt_pk_bf16_f32 v8, v8, v9
	s_waitcnt lgkmcnt(2)
	v_cvt_pk_bf16_f32 v9, v10, v11
	s_waitcnt lgkmcnt(1)
	v_cvt_pk_bf16_f32 v10, v12, v13
	s_waitcnt lgkmcnt(0)
	v_cvt_pk_bf16_f32 v11, v14, v15
	global_store_dwordx4 v[16:17], v[8:11], off
	ds_read2_b32 v[46:47], v45 offset1:65
	ds_read2_b32 v[48:49], v45 offset0:130 offset1:195
	ds_read2_b32 v[50:51], v60 offset0:4 offset1:69
	ds_read2_b32 v[52:53], v60 offset0:134 offset1:199
	v_lshl_add_u64 v[58:59], v[16:17], 0, s[98:99]
	s_waitcnt lgkmcnt(0)
	v_cvt_pk_bf16_f32 v54, v46, v47
	v_cvt_pk_bf16_f32 v55, v48, v49
	v_cvt_pk_bf16_f32 v56, v50, v51
	v_cvt_pk_bf16_f32 v57, v52, v53
	global_store_dwordx4 v[58:59], v[54:57], off
	s_barrier

.LBB0_37:
	v_mov_b32_e32 v7, v209
	s_and_b32 s8, s58, 0x3c0
	s_and_b32 s24, s59, 0x3c0
	s_xor_b32 s8, s8, 0x200
	v_ashrrev_i32_e32 v16, 4, v7
	s_lshl_b32 s22, s24, 2
	s_add_u32 s22, s51, s22
	v_lshlrev_b32_e32 v2, 4, v7
	v_add_u32_e32 v14, s8, v16
	s_addc_u32 s23, s52, 0
	v_and_b32_e32 v2, 0xf0, v2
	v_ashrrev_i32_e32 v15, 31, v14
	v_lshl_add_u64 v[12:13], s[22:23], 0, v[2:3]
	v_lshlrev_b64 v[8:9], 12, v[14:15]
	v_add_u32_e32 v14, 32, v14
	v_lshl_add_u64 v[8:9], v[12:13], 0, v[8:9]
	v_ashrrev_i32_e32 v15, 31, v14
	s_mov_b64 s[94:95], 0x400000
	v_lshl_add_u64 v[30:31], v[8:9], 0, s[94:95]
	global_load_dwordx4 v[8:11], v[8:9], off
	v_lshlrev_b64 v[14:15], 12, v[14:15]
	v_lshl_add_u64 v[12:13], v[12:13], 0, v[14:15]
	v_lshl_add_u64 v[32:33], v[12:13], 0, s[94:95]
	global_load_dwordx4 v[12:15], v[12:13], off
	global_load_dwordx4 v[34:37], v[30:31], off
	global_load_dwordx4 v[38:41], v[32:33], off
	v_ashrrev_i32_e32 v17, 3, v7
	v_lshlrev_b32_e32 v7, 3, v7
	v_mul_lo_u32 v16, v16, s29
	v_add_u32_e32 v18, s24, v17
	v_and_b32_e32 v7, 56, v7
	v_lshlrev_b32_e32 v19, 2, v17
	v_lshrrev_b32_e32 v17, 1, v17
	v_add3_u32 v20, 0, v2, v16
	v_mul_u32_u24_e32 v16, 0x104, v7
	v_lshlrev_b32_e32 v21, 2, v18
	v_and_b32_e32 v17, 12, v17
	v_and_b32_e32 v18, 0xffffffe3, v18
	v_add3_u32 v19, 0, v16, v19
	v_and_b32_e32 v16, 16, v21
	v_lshlrev_b32_e32 v2, 1, v7
	v_add_u32_e32 v7, 0x2080, v20
	v_add_u32_e32 v22, 0x2088, v20
	v_add_u32_e32 v21, 0x400, v19
	v_or3_b32 v16, v18, v17, v16
	v_ashrrev_i32_e32 v17, 31, v16
	v_lshlrev_b64 v[16:17], 11, v[16:17]
	s_lshl_b32 s8, s8, 1
	v_lshl_add_u64 v[16:17], s[20:21], 0, v[16:17]
	v_lshl_add_u64 v[16:17], v[16:17], 0, s[8:9]
	v_lshl_add_u64 v[16:17], v[16:17], 0, v[2:3]
	s_mov_b64 s[22:23], -1
	s_waitcnt vmcnt(3)
	ds_write2_b32 v20, v8, v9 offset1:1
	ds_write2_b32 v20, v10, v11 offset0:2 offset1:3
	s_waitcnt vmcnt(2)
	ds_write2_b32 v7, v12, v13 offset1:1
	ds_write2_b32 v22, v14, v15 offset1:1
	s_waitcnt vmcnt(1)
	v_add_u32_e32 v42, 0x4200, v20
	v_add_u32_e32 v43, 0x4200, v7
	v_add_u32_e32 v44, 0x4200, v22
	ds_write2_b32 v42, v34, v35 offset1:1
	ds_write2_b32 v42, v36, v37 offset0:2 offset1:3
	s_waitcnt vmcnt(0)
	ds_write2_b32 v43, v38, v39 offset1:1
	ds_write2_b32 v44, v40, v41 offset1:1
	v_add_u32_e32 v45, 0x4200, v19
	v_add_u32_e32 v60, 0x4200, v21
	s_waitcnt lgkmcnt(0)
	s_barrier
	ds_read2_b32 v[8:9], v19 offset1:65
	ds_read2_b32 v[10:11], v19 offset0:130 offset1:195
	ds_read2_b32 v[12:13], v21 offset0:4 offset1:69
	ds_read2_b32 v[14:15], v21 offset0:134 offset1:199
	s_waitcnt lgkmcnt(3)
	v_cvt_pk_bf16_f32 v8, v8, v9
	s_waitcnt lgkmcnt(2)
	v_cvt_pk_bf16_f32 v9, v10, v11
	s_waitcnt lgkmcnt(1)
	v_cvt_pk_bf16_f32 v10, v12, v13
	s_waitcnt lgkmcnt(0)
	v_cvt_pk_bf16_f32 v11, v14, v15
	global_store_dwordx4 v[16:17], v[8:11], off
	ds_read2_b32 v[46:47], v45 offset1:65
	ds_read2_b32 v[48:49], v45 offset0:130 offset1:195
	ds_read2_b32 v[50:51], v60 offset0:4 offset1:69
	ds_read2_b32 v[52:53], v60 offset0:134 offset1:199
	v_lshl_add_u64 v[58:59], v[16:17], 0, s[98:99]
	s_waitcnt lgkmcnt(0)
	v_cvt_pk_bf16_f32 v54, v46, v47
	v_cvt_pk_bf16_f32 v55, v48, v49
	v_cvt_pk_bf16_f32 v56, v50, v51
	v_cvt_pk_bf16_f32 v57, v52, v53
	global_store_dwordx4 v[58:59], v[54:57], off
	s_barrier

.LBB0_39:
	s_mov_b64 s[24:25], -1
	s_and_b64 vcc, exec, s[10:11]
	s_cbranch_vccz .LBB0_41
	s_mul_hi_i32 s8, s60, 0x2aaaaaab
	s_lshr_b32 s22, s8, 31
	s_ashr_i32 s8, s8, 2
	s_add_i32 s8, s8, s22
	s_mul_i32 s23, s8, 0xfffffa00
	s_add_i32 s24, s59, s23
	s_ashr_i32 s25, s24, 31
	v_mov_b32_e32 v7, v209
	s_lshl_b32 s22, s8, 6
	s_lshl_b64 s[24:25], s[24:25], 2
	s_add_u32 s24, s53, s24
	v_lshlrev_b32_e32 v2, 4, v7
	v_ashrrev_i32_e32 v16, 4, v7
	s_addc_u32 s25, s54, s25
	v_and_b32_e32 v2, 0xf0, v2
	v_lshl_add_u64 v[12:13], s[24:25], 0, v[2:3]
	v_add_u32_e32 v14, s22, v16
	v_mad_i64_i32 v[8:9], s[24:25], v14, s34, v[12:13]
	s_mov_b64 s[94:95], 0x600000
	v_lshl_add_u64 v[30:31], v[8:9], 0, s[94:95]
	global_load_dwordx4 v[8:11], v[8:9], off
	v_add_u32_e32 v14, 32, v14
	v_mad_i64_i32 v[12:13], s[24:25], v14, s34, v[12:13]
	v_lshl_add_u64 v[32:33], v[12:13], 0, s[94:95]
	global_load_dwordx4 v[12:15], v[12:13], off
	global_load_dwordx4 v[34:37], v[30:31], off
	global_load_dwordx4 v[38:41], v[32:33], off
	v_ashrrev_i32_e32 v17, 3, v7
	v_lshlrev_b32_e32 v18, 3, v7
	v_mul_lo_u32 v16, v16, s29
	s_mulk_i32 s8, 0x600
	v_and_b32_e32 v18, 56, v18
	v_add3_u32 v22, 0, v2, v16
	v_subrev_u32_e32 v2, s8, v17
	v_lshlrev_b32_e32 v19, 2, v17
	v_mul_u32_u24_e32 v16, 0x104, v18
	v_add_u32_e32 v2, s59, v2
	v_lshrrev_b32_e32 v20, 4, v17
	v_bfe_u32 v21, v17, 3, 1
	v_add3_u32 v19, 0, v16, v19
	v_lshrrev_b32_e32 v16, 1, v2
	v_lshlrev_b32_e32 v24, 2, v2
	v_and_b32_e32 v2, 0xffffff03, v2
	v_and_or_b32 v17, v20, 2, v21
	v_and_or_b32 v2, v7, s31, v2
	v_and_b32_e32 v16, 0x60, v16
	v_and_b32_e32 v24, 16, v24
	v_lshl_or_b32 v2, v17, 2, v2
	v_add_u32_e32 v20, 0x2080, v22
	v_add_u32_e32 v21, 0x2088, v22
	v_add_u32_e32 v23, 0x400, v19
	v_or3_b32 v16, v2, v16, v24
	v_ashrrev_i32_e32 v17, 31, v16
	v_lshlrev_b64 v[16:17], 11, v[16:17]
	s_ashr_i32 s23, s22, 31
	v_lshl_add_u64 v[16:17], s[12:13], 0, v[16:17]
	v_lshlrev_b32_e32 v2, 1, v18
	v_lshl_add_u64 v[16:17], s[22:23], 1, v[16:17]
	v_lshl_add_u64 v[16:17], v[16:17], 0, v[2:3]
	s_mov_b64 s[24:25], 0
	s_mov_b64 s[22:23], -1
	s_waitcnt vmcnt(3)
	ds_write2_b32 v22, v8, v9 offset1:1
	ds_write2_b32 v22, v10, v11 offset0:2 offset1:3
	s_waitcnt vmcnt(2)
	ds_write2_b32 v20, v12, v13 offset1:1
	ds_write2_b32 v21, v14, v15 offset1:1
	s_waitcnt vmcnt(1)
	v_add_u32_e32 v42, 0x4200, v22
	v_add_u32_e32 v43, 0x4200, v20
	v_add_u32_e32 v44, 0x4200, v21
	ds_write2_b32 v42, v34, v35 offset1:1
	ds_write2_b32 v42, v36, v37 offset0:2 offset1:3
	s_waitcnt vmcnt(0)
	ds_write2_b32 v43, v38, v39 offset1:1
	ds_write2_b32 v44, v40, v41 offset1:1
	v_add_u32_e32 v45, 0x4200, v19
	v_add_u32_e32 v60, 0x4200, v23
	s_waitcnt lgkmcnt(0)
	s_barrier
	ds_read2_b32 v[8:9], v19 offset1:65
	ds_read2_b32 v[10:11], v19 offset0:130 offset1:195
	ds_read2_b32 v[12:13], v23 offset0:4 offset1:69
	ds_read2_b32 v[14:15], v23 offset0:134 offset1:199
	s_waitcnt lgkmcnt(3)
	v_cvt_pk_bf16_f32 v8, v8, v9
	s_waitcnt lgkmcnt(2)
	v_cvt_pk_bf16_f32 v9, v10, v11
	s_waitcnt lgkmcnt(1)
	v_cvt_pk_bf16_f32 v10, v12, v13
	s_waitcnt lgkmcnt(0)
	v_cvt_pk_bf16_f32 v11, v14, v15
	global_store_dwordx4 v[16:17], v[8:11], off
	ds_read2_b32 v[46:47], v45 offset1:65
	ds_read2_b32 v[48:49], v45 offset0:130 offset1:195
	ds_read2_b32 v[50:51], v60 offset0:4 offset1:69
	ds_read2_b32 v[52:53], v60 offset0:134 offset1:199
	v_lshl_add_u64 v[58:59], v[16:17], 0, s[98:99]
	s_waitcnt lgkmcnt(0)
	v_cvt_pk_bf16_f32 v54, v46, v47
	v_cvt_pk_bf16_f32 v55, v48, v49
	v_cvt_pk_bf16_f32 v56, v50, v51
	v_cvt_pk_bf16_f32 v57, v52, v53
	global_store_dwordx4 v[58:59], v[54:57], off
	s_barrier
.LBB0_41:
	s_andn2_b64 vcc, exec, s[24:25]
	s_cbranch_vccnz .LBB0_44
	s_cmpk_lt_i32 s60, 0x140
	s_cbranch_scc0 .LBB0_44
	s_mul_hi_i32 s8, s60, 0x66666667
	s_lshr_b32 s22, s8, 31
	s_ashr_i32 s8, s8, 3
	s_add_i32 s8, s8, s22
	s_mul_i32 s23, s8, 0xfffffb00
	s_add_i32 s24, s59, s23
	s_ashr_i32 s25, s24, 31
	v_mov_b32_e32 v7, v209
	s_lshl_b32 s22, s8, 6
	s_lshl_b64 s[24:25], s[24:25], 2
	s_add_u32 s24, s55, s24
	v_lshlrev_b32_e32 v2, 4, v7
	v_ashrrev_i32_e32 v16, 4, v7
	s_addc_u32 s25, s56, s25
	v_and_b32_e32 v2, 0xf0, v2
	v_lshl_add_u64 v[12:13], s[24:25], 0, v[2:3]
	v_add_u32_e32 v14, s22, v16
	v_mad_i64_i32 v[8:9], s[24:25], v14, s35, v[12:13]
	s_mov_b64 s[94:95], 0x500000
	v_lshl_add_u64 v[30:31], v[8:9], 0, s[94:95]
	global_load_dwordx4 v[8:11], v[8:9], off
	v_add_u32_e32 v14, 32, v14
	v_mad_i64_i32 v[12:13], s[24:25], v14, s35, v[12:13]
	v_lshl_add_u64 v[32:33], v[12:13], 0, s[94:95]
	global_load_dwordx4 v[12:15], v[12:13], off
	global_load_dwordx4 v[34:37], v[30:31], off
	global_load_dwordx4 v[38:41], v[32:33], off
	v_ashrrev_i32_e32 v17, 3, v7
	v_lshlrev_b32_e32 v18, 3, v7
	v_mul_lo_u32 v16, v16, s29
	s_mulk_i32 s8, 0x500
	v_and_b32_e32 v18, 56, v18
	v_add3_u32 v22, 0, v2, v16
	v_subrev_u32_e32 v2, s8, v17
	v_lshlrev_b32_e32 v19, 2, v17
	v_mul_u32_u24_e32 v16, 0x104, v18
	v_add_u32_e32 v2, s59, v2
	v_lshrrev_b32_e32 v20, 4, v17
	v_bfe_u32 v21, v17, 3, 1
	v_add3_u32 v19, 0, v16, v19
	v_lshrrev_b32_e32 v16, 1, v2
	v_lshlrev_b32_e32 v24, 2, v2
	v_and_b32_e32 v2, 0xffffff03, v2
	v_and_or_b32 v17, v20, 2, v21
	v_and_or_b32 v2, v7, s31, v2
	v_and_b32_e32 v16, 0x60, v16
	v_and_b32_e32 v24, 16, v24
	v_lshl_or_b32 v2, v17, 2, v2
	v_add_u32_e32 v20, 0x2080, v22
	v_add_u32_e32 v21, 0x2088, v22
	v_add_u32_e32 v23, 0x400, v19
	v_or3_b32 v16, v2, v16, v24
	v_ashrrev_i32_e32 v17, 31, v16
	v_lshlrev_b64 v[16:17], 11, v[16:17]
	s_ashr_i32 s23, s22, 31
	v_lshl_add_u64 v[16:17], s[12:13], 0, v[16:17]
	v_lshlrev_b32_e32 v2, 1, v18
	v_lshl_add_u64 v[16:17], s[22:23], 1, v[16:17]
	v_lshl_add_u64 v[16:17], v[16:17], 0, v[2:3]
	s_mov_b64 s[22:23], -1
	s_waitcnt vmcnt(3)
	ds_write2_b32 v22, v8, v9 offset1:1
	ds_write2_b32 v22, v10, v11 offset0:2 offset1:3
	s_waitcnt vmcnt(2)
	ds_write2_b32 v20, v12, v13 offset1:1
	ds_write2_b32 v21, v14, v15 offset1:1
	s_waitcnt vmcnt(1)
	v_add_u32_e32 v42, 0x4200, v22
	v_add_u32_e32 v43, 0x4200, v20
	v_add_u32_e32 v44, 0x4200, v21
	ds_write2_b32 v42, v34, v35 offset1:1
	ds_write2_b32 v42, v36, v37 offset0:2 offset1:3
	s_waitcnt vmcnt(0)
	ds_write2_b32 v43, v38, v39 offset1:1
	ds_write2_b32 v44, v40, v41 offset1:1
	v_add_u32_e32 v45, 0x4200, v19
	v_add_u32_e32 v60, 0x4200, v23
	s_waitcnt lgkmcnt(0)
	s_barrier
	ds_read2_b32 v[8:9], v19 offset1:65
	ds_read2_b32 v[10:11], v19 offset0:130 offset1:195
	ds_read2_b32 v[12:13], v23 offset0:4 offset1:69
	ds_read2_b32 v[14:15], v23 offset0:134 offset1:199
	s_waitcnt lgkmcnt(3)
	v_cvt_pk_bf16_f32 v8, v8, v9
	s_waitcnt lgkmcnt(2)
	v_cvt_pk_bf16_f32 v9, v10, v11
	s_waitcnt lgkmcnt(1)
	v_cvt_pk_bf16_f32 v10, v12, v13
	s_waitcnt lgkmcnt(0)
	v_cvt_pk_bf16_f32 v11, v14, v15
	global_store_dwordx4 v[16:17], v[8:11], off
	ds_read2_b32 v[46:47], v45 offset1:65
	ds_read2_b32 v[48:49], v45 offset0:130 offset1:195
	ds_read2_b32 v[50:51], v60 offset0:4 offset1:69
	ds_read2_b32 v[52:53], v60 offset0:134 offset1:199
	v_lshl_add_u64 v[58:59], v[16:17], 0, s[98:99]
	s_waitcnt lgkmcnt(0)
	v_cvt_pk_bf16_f32 v54, v46, v47
	v_cvt_pk_bf16_f32 v55, v48, v49
	v_cvt_pk_bf16_f32 v56, v50, v51
	v_cvt_pk_bf16_f32 v57, v52, v53
	global_store_dwordx4 v[58:59], v[54:57], off
	s_barrier
